# grid barrier: every 8th arriving WG per XCD issues an early L2 writeback (4 per XCD)
# baseline (speedup 1.0000x reference)
; __device__ __forceinline__ unsigned xb_ld(unsigned* p)              { return __hip_atomic_load(p, __ATOMIC_RELAXED, __HIP_MEMORY_SCOPE_AGENT); }
; __device__ __forceinline__ unsigned xb_add(unsigned* p, unsigned v) { return __hip_atomic_fetch_add(p, v, __ATOMIC_RELAXED, __HIP_MEMORY_SCOPE_AGENT); }
; #define XB_SPIN(cond, bar) do { unsigned _sp = 0; while (cond) { __builtin_amdgcn_s_sleep(1); \
;     if ((++_sp & 255u) == 0u) { if (xb_ld(&(bar)[XB_TMO])) break; if (_sp > XB_SPIN_CAP) { atomicAdd(&(bar)[XB_TMO], 1u); break; } } } } while (0)
; __device__ __forceinline__ void xcd_barrier(const XcdBarrier& b) {
;     ...
;         const unsigned old = xb_add(&bar[XB_XSUB(b.x)], 1u);
;         const unsigned gen = old / nloc;
;         if (old + 1u == (gen + 1u) * nloc) {
;             __builtin_amdgcn_fence(__ATOMIC_RELEASE, "agent");
;             asm volatile("s_waitcnt vmcnt(0)" ::: "memory");
;             const unsigned og = xb_add(&bar[XB_TOP], 1u);
;             const unsigned tg = og / nx;
;             if (og + 1u == (tg + 1u) * nx) xb_add(&bar[XB_TOPGEN], 1u);
;             else XB_SPIN(xb_ld(&bar[XB_TOPGEN]) == tg, bar);
;             __builtin_amdgcn_fence(__ATOMIC_ACQUIRE, "agent");
;             xb_add(&bar[XB_XGEN(b.x)], 1u);
;             asm volatile("s_waitcnt vmcnt(0)" ::: "memory");
;         } else {
;             XB_SPIN(xb_ld(&bar[XB_XGEN(b.x)]) == gen, bar);
.LBB0_151:
	s_or_b64 exec, exec, s[24:25]
	v_cvt_f32_u32_e32 v5, v3
	s_waitcnt vmcnt(0)
	v_readfirstlane_b32 s24, v4
	v_sub_u32_e32 v4, 0, v3
	v_rcp_iflag_f32_e32 v5, v5
	v_add_u32_e32 v6, s24, v0
	v_mul_f32_e32 v5, 0x4f7ffffe, v5
	v_cvt_u32_f32_e32 v5, v5
	v_mul_lo_u32 v0, v4, v5
	v_mul_hi_u32 v0, v5, v0
	v_add_u32_e32 v0, v5, v0
	v_mul_hi_u32 v0, v6, v0
	v_mul_lo_u32 v4, v0, v3
	v_sub_u32_e32 v4, v6, v4
	v_add_u32_e32 v5, 1, v0
	v_cmp_ge_u32_e32 vcc, v4, v3
	s_nop 1
	v_cndmask_b32_e32 v0, v0, v5, vcc
	v_sub_u32_e32 v5, v4, v3
	v_cndmask_b32_e32 v4, v4, v5, vcc
	v_add_u32_e32 v5, 1, v0
	v_cmp_ge_u32_e32 vcc, v4, v3
	v_add_u32_e32 v4, 1, v6
	s_nop 0
	v_cndmask_b32_e32 v0, v0, v5, vcc
	v_mul_lo_u32 v5, v3, v0
	v_add_u32_e32 v3, v5, v3
	v_cmp_ne_u32_e32 vcc, v4, v3
	s_and_saveexec_b64 s[24:25], vcc
	s_xor_b64 s[24:25], exec, s[24:25]
	s_cbranch_execz .LBB0_165
	v_sub_u32_e32 v2, v6, v5
	v_and_b32_e32 v2, 7, v2
	v_cmp_eq_u32_e32 vcc, 0, v2
	s_and_saveexec_b64 s[100:101], vcc
	s_cbranch_execz .Lmy_ewb_0
	buffer_wbl2 sc1
.Lmy_ewb_0:
	s_or_b64 exec, exec, s[100:101]
	v_readlane_b32 s26, v252, 63
	v_readlane_b32 s27, v253, 0
	s_waitcnt lgkmcnt(0)
	s_nop 3
	global_load_dword v2, v1, s[26:27] sc1
	s_waitcnt vmcnt(0)
	v_cmp_eq_u32_e32 vcc, v2, v0
	s_and_saveexec_b64 s[26:27], vcc
	s_cbranch_execz .LBB0_164
	s_mov_b32 s34, 1
	s_mov_b64 s[28:29], 0
	s_branch .LBB0_155

; __device__ __forceinline__ unsigned xb_ld(unsigned* p)              { return __hip_atomic_load(p, __ATOMIC_RELAXED, __HIP_MEMORY_SCOPE_AGENT); }
; __device__ __forceinline__ unsigned xb_add(unsigned* p, unsigned v) { return __hip_atomic_fetch_add(p, v, __ATOMIC_RELAXED, __HIP_MEMORY_SCOPE_AGENT); }
; #define XB_SPIN(cond, bar) do { unsigned _sp = 0; while (cond) { __builtin_amdgcn_s_sleep(1); \
;     if ((++_sp & 255u) == 0u) { if (xb_ld(&(bar)[XB_TMO])) break; if (_sp > XB_SPIN_CAP) { atomicAdd(&(bar)[XB_TMO], 1u); break; } } } } while (0)
; __device__ __forceinline__ void xcd_barrier(const XcdBarrier& b) {
;     ...
;         const unsigned old = xb_add(&bar[XB_XSUB(b.x)], 1u);
;         const unsigned gen = old / nloc;
;         if (old + 1u == (gen + 1u) * nloc) {
;             __builtin_amdgcn_fence(__ATOMIC_RELEASE, "agent");
;             asm volatile("s_waitcnt vmcnt(0)" ::: "memory");
;             const unsigned og = xb_add(&bar[XB_TOP], 1u);
;             const unsigned tg = og / nx;
;             if (og + 1u == (tg + 1u) * nx) xb_add(&bar[XB_TOPGEN], 1u);
;             else XB_SPIN(xb_ld(&bar[XB_TOPGEN]) == tg, bar);
;             __builtin_amdgcn_fence(__ATOMIC_ACQUIRE, "agent");
;             xb_add(&bar[XB_XGEN(b.x)], 1u);
;             asm volatile("s_waitcnt vmcnt(0)" ::: "memory");
;         } else {
;             XB_SPIN(xb_ld(&bar[XB_XGEN(b.x)]) == gen, bar);
.LBB0_354:
	s_or_b64 exec, exec, s[2:3]
	v_cvt_f32_u32_e32 v5, v3
	s_waitcnt vmcnt(0)
	v_readfirstlane_b32 s2, v4
	v_sub_u32_e32 v4, 0, v3
	v_rcp_iflag_f32_e32 v5, v5
	v_add_u32_e32 v6, s2, v0
	v_mul_f32_e32 v5, 0x4f7ffffe, v5
	v_cvt_u32_f32_e32 v5, v5
	v_mul_lo_u32 v0, v4, v5
	v_mul_hi_u32 v0, v5, v0
	v_add_u32_e32 v0, v5, v0
	v_mul_hi_u32 v0, v6, v0
	v_mul_lo_u32 v4, v0, v3
	v_sub_u32_e32 v4, v6, v4
	v_add_u32_e32 v5, 1, v0
	v_cmp_ge_u32_e32 vcc, v4, v3
	s_nop 1
	v_cndmask_b32_e32 v0, v0, v5, vcc
	v_sub_u32_e32 v5, v4, v3
	v_cndmask_b32_e32 v4, v4, v5, vcc
	v_add_u32_e32 v5, 1, v0
	v_cmp_ge_u32_e32 vcc, v4, v3
	v_add_u32_e32 v4, 1, v6
	s_nop 0
	v_cndmask_b32_e32 v0, v0, v5, vcc
	v_mul_lo_u32 v5, v3, v0
	v_add_u32_e32 v3, v5, v3
	v_cmp_ne_u32_e32 vcc, v4, v3
	s_and_saveexec_b64 s[2:3], vcc
	s_xor_b64 s[2:3], exec, s[2:3]
	s_cbranch_execz .LBB0_368
	v_sub_u32_e32 v2, v6, v5
	v_and_b32_e32 v2, 7, v2
	v_cmp_eq_u32_e32 vcc, 0, v2
	s_and_saveexec_b64 s[100:101], vcc
	s_cbranch_execz .Lmy_ewb_2
	buffer_wbl2 sc1
.Lmy_ewb_2:
	s_or_b64 exec, exec, s[100:101]
	v_readlane_b32 s24, v252, 63
	v_readlane_b32 s25, v253, 0
	s_waitcnt lgkmcnt(0)
	s_nop 3
	global_load_dword v2, v1, s[24:25] sc1
	s_waitcnt vmcnt(0)
	v_cmp_eq_u32_e32 vcc, v2, v0
	s_and_saveexec_b64 s[24:25], vcc
	s_cbranch_execz .LBB0_367
	s_mov_b32 s34, 1
	s_mov_b64 s[26:27], 0
	s_branch .LBB0_358
